# P4 p->bf16 conversion loads batched (16 in flight, cvt_pk), P0 GT copy loads batched
# speedup vs baseline: 1.0252x; 1.0005x over previous
; __global__ void __launch_bounds__(NWAVES * 64, 2) fwd_megakernel(Args args) {
;     ...
;         if (gw == 0) { float* GT = (float*)(ws + WS_GT); GT[lane] = g_q_win[lane]; GT[64 + lane] = g_k_win[lane]; GT[128 + lane] = g_q_band[lane]; GT[192 + lane] = g_k_band[lane]; }
.LBB0_42:
	s_waitcnt lgkmcnt(0)
	s_load_dwordx16 s[64:79], s[0:1], 0x0
	s_cmp_eq_u32 s3, 0
	s_cbranch_scc0 .LBB0_44
	v_lshlrev_b32_e32 v2, 2, v68
	global_load_dword v1, v2, s[80:81]
	global_load_dword v8, v2, s[82:83]
	global_load_dword v9, v2, s[86:87]
	global_load_dword v10, v2, s[88:89]
	v_mov_b32_e32 v3, 0
	v_lshl_add_u64 v[4:5], s[62:63], 0, v[2:3]
	v_add_co_u32_e32 v6, vcc, 0x100000, v4
	s_mov_b64 s[0:1], 0x100000
	s_nop 0
	v_addc_co_u32_e32 v7, vcc, 0, v5, vcc
	v_lshl_add_u64 v[4:5], v[4:5], 0, s[0:1]
	s_waitcnt vmcnt(3)
	global_store_dword v[6:7], v1, off
	s_waitcnt vmcnt(3)
	global_store_dword v[4:5], v8, off offset:256
	s_waitcnt vmcnt(3)
	global_store_dword v[4:5], v9, off offset:512
	s_waitcnt vmcnt(3)
	global_store_dword v[4:5], v10, off offset:768

; __device__ __forceinline__ unsigned pk2(float lo, float hi) { return f2bf(lo) | (f2bf(hi) << 16); }
; __global__ void __launch_bounds__(NWAVES * 64, 2) fwd_megakernel(Args args) {
;     ...
;         for (int m0 = gw * 4; m0 < MP; m0 += NGW * 4) {
;             f32x4 v[4];
; #pragma unroll
;             for (int q = 0; q < 4; ++q) v[q] = __builtin_nontemporal_load((const f32x4*)(p_prompt + (size_t)(m0 + q) * 256) + lane);
; #pragma unroll
;             for (int q = 0; q < 4; ++q) { u32x2 w; w.x = pk2(v[q][0], v[q][1]); w.y = pk2(v[q][2], v[q][3]); *((u32x2*)(HP + (size_t)(m0 + q) * LDHP + 1024) + lane) = w; }
;         }
.LBB0_878:
	s_or_b64 exec, exec, s[0:1]
	s_waitcnt lgkmcnt(0)
	v_mov_b32_e32 v1, v0
	s_barrier
	s_nop 0
	v_readfirstlane_b32 s0, v1
	s_ashr_i32 s2, s0, 6
	v_readlane_b32 s0, v254, 6
	v_and_b32_e32 v2, 63, v1
	s_add_i32 s3, s2, s0
	s_cmpk_gt_i32 s3, 0x1fff
	v_lshlrev_b32_e32 v4, 3, v2
	v_lshlrev_b32_e32 v2, 4, v2
	s_cbranch_scc1 .LBB0_881
	s_lshl_b32 s4, s3, 2
	s_lshl_b32 s0, s93, 5
	s_ashr_i32 s5, s4, 31
	s_mul_i32 s1, s3, 0x2800
	s_mul_hi_i32 s7, s4, 0xa00
	s_add_u32 s6, s62, s1
	s_addc_u32 s7, s63, s7
	s_ashr_i32 s1, s0, 31
	s_lshl_b64 s[8:9], s[4:5], 10
	v_mov_b32_e32 v5, 0
	s_add_u32 s8, s76, s8
	v_mov_b32_e32 v3, v5
	s_addc_u32 s9, s77, s9
	v_lshl_add_u64 v[6:7], s[6:7], 0, v[4:5]
	s_mov_b64 s[6:7], 0x5a00800
	v_lshl_add_u64 v[8:9], s[8:9], 0, v[2:3]
	s_mov_b64 s[8:9], 0xc00
	v_lshl_add_u64 v[6:7], v[6:7], 0, s[6:7]
	s_mul_i32 s6, s93, 0x14000
	s_mul_hi_i32 s7, s0, 0xa00
	v_lshl_add_u64 v[8:9], v[8:9], 0, s[8:9]
	s_lshl_b64 s[8:9], s[0:1], 10
	s_movk_i32 s1, 0x7fff
	s_mov_b32 s5, 0xffff0000
	s_movk_i32 s10, 0x1000
	s_mul_i32 s11, s0, 3
	s_add_i32 s11, s11, s4
	s_cmp_lt_i32 s11, 0x8000
	s_mov_b32 s11, 0
	s_cbranch_scc0 .LBB0_880
	v_lshl_add_u64 v[74:75], v[8:9], 0, s[8:9]
	v_lshl_add_u64 v[76:77], v[74:75], 0, s[8:9]
	v_lshl_add_u64 v[78:79], v[76:77], 0, s[8:9]
	global_load_dwordx4 v[10:13], v[8:9], off offset:-3072 nt
	global_load_dwordx4 v[14:17], v[8:9], off offset:-2048 nt
	global_load_dwordx4 v[18:21], v[8:9], off offset:-1024 nt
	global_load_dwordx4 v[22:25], v[8:9], off nt
	global_load_dwordx4 v[26:29], v[74:75], off offset:-3072 nt
	global_load_dwordx4 v[30:33], v[74:75], off offset:-2048 nt
	global_load_dwordx4 v[34:37], v[74:75], off offset:-1024 nt
	global_load_dwordx4 v[38:41], v[74:75], off nt
	global_load_dwordx4 v[42:45], v[76:77], off offset:-3072 nt
	global_load_dwordx4 v[46:49], v[76:77], off offset:-2048 nt
	global_load_dwordx4 v[50:53], v[76:77], off offset:-1024 nt
	global_load_dwordx4 v[54:57], v[76:77], off nt
	global_load_dwordx4 v[58:61], v[78:79], off offset:-3072 nt
	global_load_dwordx4 v[62:65], v[78:79], off offset:-2048 nt
	global_load_dwordx4 v[66:69], v[78:79], off offset:-1024 nt
	global_load_dwordx4 v[70:73], v[78:79], off nt
	v_lshl_add_u64 v[80:81], v[6:7], 0, s[10:11]
	s_waitcnt vmcnt(15)
	v_cvt_pk_bf16_f32 v82, v10, v11
	v_cvt_pk_bf16_f32 v83, v12, v13
	global_store_dwordx2 v[6:7], v[82:83], off
	s_waitcnt vmcnt(15)
	v_cvt_pk_bf16_f32 v84, v14, v15
	v_cvt_pk_bf16_f32 v85, v16, v17
	global_store_dwordx2 v[6:7], v[84:85], off offset:2560
	s_waitcnt vmcnt(15)
	v_cvt_pk_bf16_f32 v82, v18, v19
	v_cvt_pk_bf16_f32 v83, v20, v21
	global_store_dwordx2 v[80:81], v[82:83], off offset:1024
	s_waitcnt vmcnt(15)
	v_cvt_pk_bf16_f32 v84, v22, v23
	v_cvt_pk_bf16_f32 v85, v24, v25
	global_store_dwordx2 v[80:81], v[84:85], off offset:3584
	v_lshl_add_u64 v[6:7], v[6:7], 0, s[6:7]
	v_lshl_add_u64 v[80:81], v[6:7], 0, s[10:11]
	s_waitcnt vmcnt(15)
	v_cvt_pk_bf16_f32 v82, v26, v27
	v_cvt_pk_bf16_f32 v83, v28, v29
	global_store_dwordx2 v[6:7], v[82:83], off
	s_waitcnt vmcnt(15)
	v_cvt_pk_bf16_f32 v84, v30, v31
	v_cvt_pk_bf16_f32 v85, v32, v33
	global_store_dwordx2 v[6:7], v[84:85], off offset:2560
	s_waitcnt vmcnt(15)
	v_cvt_pk_bf16_f32 v82, v34, v35
	v_cvt_pk_bf16_f32 v83, v36, v37
	global_store_dwordx2 v[80:81], v[82:83], off offset:1024
	s_waitcnt vmcnt(15)
	v_cvt_pk_bf16_f32 v84, v38, v39
	v_cvt_pk_bf16_f32 v85, v40, v41
	global_store_dwordx2 v[80:81], v[84:85], off offset:3584
	v_lshl_add_u64 v[6:7], v[6:7], 0, s[6:7]
	v_lshl_add_u64 v[80:81], v[6:7], 0, s[10:11]
	s_waitcnt vmcnt(15)
	v_cvt_pk_bf16_f32 v82, v42, v43
	v_cvt_pk_bf16_f32 v83, v44, v45
	global_store_dwordx2 v[6:7], v[82:83], off
	s_waitcnt vmcnt(15)
	v_cvt_pk_bf16_f32 v84, v46, v47
	v_cvt_pk_bf16_f32 v85, v48, v49
	global_store_dwordx2 v[6:7], v[84:85], off offset:2560
	s_waitcnt vmcnt(15)
	v_cvt_pk_bf16_f32 v82, v50, v51
	v_cvt_pk_bf16_f32 v83, v52, v53
	global_store_dwordx2 v[80:81], v[82:83], off offset:1024
	s_waitcnt vmcnt(15)
	v_cvt_pk_bf16_f32 v84, v54, v55
	v_cvt_pk_bf16_f32 v85, v56, v57
	global_store_dwordx2 v[80:81], v[84:85], off offset:3584
	v_lshl_add_u64 v[6:7], v[6:7], 0, s[6:7]
	v_lshl_add_u64 v[80:81], v[6:7], 0, s[10:11]
	s_waitcnt vmcnt(15)
	v_cvt_pk_bf16_f32 v82, v58, v59
	v_cvt_pk_bf16_f32 v83, v60, v61
	global_store_dwordx2 v[6:7], v[82:83], off
	s_waitcnt vmcnt(15)
	v_cvt_pk_bf16_f32 v84, v62, v63
	v_cvt_pk_bf16_f32 v85, v64, v65
	global_store_dwordx2 v[6:7], v[84:85], off offset:2560
	s_waitcnt vmcnt(15)
	v_cvt_pk_bf16_f32 v82, v66, v67
	v_cvt_pk_bf16_f32 v83, v68, v69
	global_store_dwordx2 v[80:81], v[82:83], off offset:1024
	s_waitcnt vmcnt(15)
	v_cvt_pk_bf16_f32 v84, v70, v71
	v_cvt_pk_bf16_f32 v85, v72, v73
	global_store_dwordx2 v[80:81], v[84:85], off offset:3584
	s_branch .LBB0_881
